# w_o decode-row exchanges: the 8 partner slots of a lane polled together (four 16-byte loads) instead of one after another
# speedup vs baseline: 1.0078x; 1.0010x over previous
.LBB0_876:
	s_or_b64 exec, exec, s[24:25]
	v_lshlrev_b32_e32 v8, 3, v12
	v_lshl_add_u64 v[28:29], s[0:1], 0, v[8:9]
	v_lshlrev_b32_e32 v18, 3, v0
	v_mov_b32_e32 v19, v9
	s_lshl_b32 s17, s40, 9
	v_lshl_add_u64 v[28:29], v[28:29], 0, v[18:19]
	s_waitcnt lgkmcnt(0)
	s_mov_b32 s24, 0
.Lxch8_wo1_poll:
	global_load_dwordx4 v[200:203], v[28:29], off sc1
	global_load_dwordx4 v[204:207], v[28:29], off offset:16 sc1
	global_load_dwordx4 v[208:211], v[28:29], off offset:32 sc1
	global_load_dwordx4 v[212:215], v[28:29], off offset:48 sc1
	s_waitcnt vmcnt(0)
	v_min3_u32 v216, v201, v203, v205
	v_min3_u32 v216, v216, v207, v209
	v_min3_u32 v216, v216, v211, v213
	v_min_u32_e32 v216, v216, v215
	v_cmp_eq_u32_e32 vcc, 0, v216
	s_cbranch_vccz .Lxch8_wo1_ready
	s_add_i32 s24, s24, 1
	s_cmp_lt_u32 s24, 0x400000
	s_cbranch_scc0 .Lxch8_wo1_ready
	s_sleep 1
	s_branch .Lxch8_wo1_poll
.Lxch8_wo1_ready:
	v_mov_b32_e32 v14, v200
	v_mov_b32_e32 v17, v202
	v_mov_b32_e32 v19, v204
	v_mov_b32_e32 v39, v206
	v_mov_b32_e32 v40, v208
	v_mov_b32_e32 v41, v210
	v_mov_b32_e32 v42, v212
	v_mov_b32_e32 v43, v214
	v_lshl_or_b32 v30, s16, 5, v0
	v_lshl_or_b32 v28, s40, 4, v1
	v_readlane_b32 s40, v252, 14
	v_ashrrev_i32_e32 v31, 31, v30
	v_lshlrev_b32_e32 v44, 12, v28
	v_mov_b32_e32 v45, v9
	v_readlane_b32 s42, v252, 16
	v_readlane_b32 s43, v252, 17
	v_readlane_b32 s50, v252, 24
	v_readlane_b32 s51, v252, 25
	v_lshl_add_u64 v[44:45], s[42:43], 0, v[44:45]
	v_lshlrev_b64 v[46:47], 2, v[30:31]
	v_lshl_add_u64 v[56:57], v[44:45], 0, v[46:47]
	v_lshl_add_u64 v[52:53], s[50:51], 0, v[46:47]
	global_load_dwordx4 v[44:47], v[56:57], off
	global_load_dwordx4 v[48:51], v[52:53], off
	s_nop 0
	global_load_dwordx4 v[52:55], v[52:53], off offset:16
	s_nop 0
	global_load_dwordx4 v[56:59], v[56:57], off offset:16
	v_add_f32_e32 v14, 0, v14
	v_add_f32_e32 v14, v14, v17
	v_add_f32_e32 v14, v14, v19
	v_add_f32_e32 v14, v14, v39
	v_add_f32_e32 v14, v14, v40
	v_add_f32_e32 v14, v14, v41
	v_add_f32_e32 v14, v14, v42
	v_add_f32_e32 v14, v14, v43
	ds_bpermute_b32 v17, v37, v14
	v_readlane_b32 s41, v252, 15
	v_readlane_b32 s44, v252, 18
	v_readlane_b32 s45, v252, 19
	v_readlane_b32 s46, v252, 20
	s_waitcnt lgkmcnt(0)
	v_add_f32_e32 v14, v14, v17
	ds_bpermute_b32 v17, v38, v14
	v_readlane_b32 s47, v252, 21
	v_readlane_b32 s40, v252, 0
	v_readlane_b32 s44, v252, 4
	v_readlane_b32 s45, v252, 5
	s_waitcnt lgkmcnt(0)
	v_add_f32_e32 v14, v14, v17
	v_fmamk_f32 v14, v14, 0x3a800000, v35
	v_mul_f32_e32 v17, 0x4f800000, v14
	v_cmp_gt_f32_e32 vcc, s35, v14
	v_readlane_b32 s46, v252, 6
	v_readlane_b32 s47, v252, 7
	v_cndmask_b32_e32 v14, v14, v17, vcc
	v_sqrt_f32_e32 v17, v14
	s_mov_b64 s[24:25], s[44:45]
	v_mov_b32_e32 v41, v9
	v_lshlrev_b32_e32 v40, 11, v28
	v_add_u32_e32 v19, -1, v17
	v_add_u32_e32 v29, 1, v17
	v_fma_f32 v39, -v19, v17, v14
	v_fma_f32 v42, -v29, v17, v14
	v_cmp_ge_f32_e64 s[0:1], 0, v39
	s_mov_b64 s[26:27], s[46:47]
	v_lshl_add_u64 v[40:41], s[26:27], 0, v[40:41]
	v_cndmask_b32_e64 v17, v17, v19, s[0:1]
	v_cmp_lt_f32_e64 s[0:1], 0, v42
	v_lshl_add_u64 v[30:31], v[30:31], 1, v[40:41]
	v_readlane_b32 s48, v252, 22
	v_cndmask_b32_e64 v17, v17, v29, s[0:1]
	v_mul_f32_e32 v19, 0x37800000, v17
	v_cndmask_b32_e32 v17, v17, v19, vcc
	v_cmp_class_f32_e32 vcc, v14, v36
	v_readlane_b32 s49, v252, 23
	v_readlane_b32 s52, v252, 26
	v_cndmask_b32_e32 v14, v17, v14, vcc
	v_div_scale_f32 v17, s[0:1], v14, v14, 1.0
	v_rcp_f32_e32 v19, v17
	v_div_scale_f32 v29, vcc, 1.0, v14, 1.0
	s_lshl_b32 s0, s17, 3
	v_fma_f32 v39, -v17, v19, 1.0
	v_fmac_f32_e32 v19, v39, v19
	v_mul_f32_e32 v39, v29, v19
	v_fma_f32 v40, -v17, v39, v29
	v_fmac_f32_e32 v39, v40, v19
	v_fma_f32 v17, -v17, v39, v29
	v_div_fmas_f32 v17, v17, v19, v39
	v_div_fixup_f32 v14, v17, v14, 1.0
	v_pk_mul_f32 v[24:25], v[24:25], v[14:15] op_sel_hi:[1,0]
	v_pk_mul_f32 v[20:21], v[20:21], v[14:15] op_sel_hi:[1,0]
	v_pk_mul_f32 v[26:27], v[26:27], v[14:15] op_sel_hi:[1,0]
	v_pk_mul_f32 v[22:23], v[22:23], v[14:15] op_sel_hi:[1,0]
	s_add_u32 s0, s26, s0
	s_addc_u32 s1, s27, 0
	s_add_u32 s0, s0, 0xe4a8000
	s_addc_u32 s1, s1, 0
	v_readlane_b32 s53, v252, 27
	v_readlane_b32 s54, v252, 28
	v_readlane_b32 s55, v252, 29
	v_readlane_b32 s41, v252, 1
	v_readlane_b32 s42, v252, 2
	v_readlane_b32 s43, v252, 3
	s_waitcnt vmcnt(2)
	v_pk_fma_f32 v[40:41], v[50:51], v[20:21], v[46:47]
	v_pk_fma_f32 v[24:25], v[48:49], v[24:25], v[44:45]
	s_waitcnt vmcnt(0)
	v_pk_fma_f32 v[42:43], v[54:55], v[22:23], v[58:59]
	v_pk_fma_f32 v[26:27], v[52:53], v[26:27], v[56:57]
	v_cvt_pk_bf16_f32 v20, v24, v25
	v_mul_f32_e32 v14, v25, v25
	v_mul_f32_e32 v17, v41, v41
	v_mul_f32_e32 v19, v27, v27
	v_mul_f32_e32 v25, v43, v43
	v_fmac_f32_e32 v14, v24, v24
	v_fmac_f32_e32 v17, v40, v40
	v_fmac_f32_e32 v19, v26, v26
	v_fmac_f32_e32 v25, v42, v42
	v_add_f32_e32 v14, v14, v17
	v_add_f32_e32 v17, v19, v25
	v_add_f32_e32 v14, v14, v17
	ds_bpermute_b32 v17, v37, v14
	v_add_co_u32_e32 v24, vcc, s36, v30
	v_cvt_pk_bf16_f32 v21, v40, v41
	v_cvt_pk_bf16_f32 v22, v26, v27
	s_waitcnt lgkmcnt(0)
	v_add_f32_e32 v14, v14, v17
	ds_bpermute_b32 v17, v38, v14
	v_addc_co_u32_e32 v25, vcc, 0, v31, vcc
	v_cvt_pk_bf16_f32 v23, v42, v43
	global_store_dwordx4 v[24:25], v[20:23], off sc0 sc1
	s_and_saveexec_b64 s[24:25], s[6:7]
	s_cbranch_execz .LBB0_942
	s_waitcnt lgkmcnt(0)
	v_add_f32_e32 v14, v14, v17
	v_mov_b32_e32 v17, v9
	v_lshl_add_u64 v[16:17], s[0:1], 0, v[16:17]
	s_ashr_i32 s17, s16, 31
	v_lshl_add_u64 v[16:17], s[16:17], 3, v[16:17]
	global_store_dwordx2 v[16:17], v[14:15], off sc1
.LBB0_942:
	s_or_b64 exec, exec, s[24:25]
	s_waitcnt lgkmcnt(0)
	v_lshl_add_u64 v[16:17], s[0:1], 0, v[8:9]
	v_mov_b32_e32 v19, v9
	v_lshl_add_u64 v[16:17], v[16:17], 0, v[18:19]
	s_waitcnt lgkmcnt(0)
	s_mov_b32 s24, 0
.Lxch8_wo2_poll:
	global_load_dwordx4 v[200:203], v[16:17], off sc1
	global_load_dwordx4 v[204:207], v[16:17], off offset:16 sc1
	global_load_dwordx4 v[208:211], v[16:17], off offset:32 sc1
	global_load_dwordx4 v[212:215], v[16:17], off offset:48 sc1
	s_waitcnt vmcnt(0)
	v_min3_u32 v216, v201, v203, v205
	v_min3_u32 v216, v216, v207, v209
	v_min3_u32 v216, v216, v211, v213
	v_min_u32_e32 v216, v216, v215
	v_cmp_eq_u32_e32 vcc, 0, v216
	s_cbranch_vccz .Lxch8_wo2_ready
	s_add_i32 s24, s24, 1
	s_cmp_lt_u32 s24, 0x400000
	s_cbranch_scc0 .Lxch8_wo2_ready
	s_sleep 1
	s_branch .Lxch8_wo2_poll
.Lxch8_wo2_ready:
	v_mov_b32_e32 v8, v200
	v_mov_b32_e32 v14, v202
	v_mov_b32_e32 v20, v204
	v_mov_b32_e32 v21, v206
	v_mov_b32_e32 v22, v208
	v_mov_b32_e32 v23, v210
	v_mov_b32_e32 v24, v212
	v_mov_b32_e32 v26, v214
	v_add_f32_e32 v8, 0, v8
	v_add_f32_e32 v8, v8, v14
	v_add_f32_e32 v8, v8, v20
	v_add_f32_e32 v8, v8, v21
	v_add_f32_e32 v8, v8, v22
	v_add_f32_e32 v8, v8, v23
	v_add_f32_e32 v8, v8, v24
	v_add_f32_e32 v8, v8, v26
	ds_bpermute_b32 v14, v37, v8
	s_cmp_lt_u32 s39, 8
	s_cselect_b64 s[0:1], -1, 0
	s_and_b64 s[0:1], s[6:7], s[0:1]
	s_waitcnt lgkmcnt(0)
	v_add_f32_e32 v8, v8, v14
	ds_bpermute_b32 v14, v38, v8
	s_and_saveexec_b64 s[16:17], s[0:1]
	s_cbranch_execz .LBB0_871
	s_waitcnt lgkmcnt(0)
	v_add_f32_e32 v8, v8, v14
	v_fmamk_f32 v8, v8, 0x3a800000, v35
	v_mul_f32_e32 v14, 0x4f800000, v8
	v_cmp_gt_f32_e32 vcc, s35, v8
	s_nop 1
	v_cndmask_b32_e32 v8, v8, v14, vcc
	v_sqrt_f32_e32 v14, v8
	s_nop 0
	v_add_u32_e32 v16, -1, v14
	v_fma_f32 v18, -v16, v14, v8
	v_add_u32_e32 v17, 1, v14
	v_cmp_ge_f32_e64 s[0:1], 0, v18
	s_nop 1
	v_cndmask_b32_e64 v16, v14, v16, s[0:1]
	v_fma_f32 v14, -v17, v14, v8
	v_cmp_lt_f32_e64 s[0:1], 0, v14
	s_nop 1
	v_cndmask_b32_e64 v14, v16, v17, s[0:1]
	v_mul_f32_e32 v16, 0x37800000, v14
	v_cndmask_b32_e32 v14, v14, v16, vcc
	v_cmp_class_f32_e32 vcc, v8, v36
	s_nop 1
	v_cndmask_b32_e32 v8, v14, v8, vcc
	v_div_scale_f32 v14, s[0:1], v8, v8, 1.0
	v_rcp_f32_e32 v16, v14
	s_nop 0
	v_fma_f32 v17, -v14, v16, 1.0
	v_fmac_f32_e32 v16, v17, v16
	v_div_scale_f32 v17, vcc, 1.0, v8, 1.0
	v_mul_f32_e32 v18, v17, v16
	v_fma_f32 v19, -v14, v18, v17
	v_fmac_f32_e32 v18, v19, v16
	v_fma_f32 v14, -v14, v18, v17
	v_div_fmas_f32 v14, v14, v16, v18
	v_div_fixup_f32 v8, v14, v8, 1.0
	v_lshlrev_b32_e32 v14, 2, v28
	global_store_dword v14, v8, s[10:11] sc0 sc1
	s_branch .LBB0_871
